# weight-conversion stores that run in the idle GEMM tails (W_in, W_rg, W_br, W_out) marked non-temporal so they do not evict the next phase's L2-resident inputs
# baseline (speedup 1.0000x reference)
; #define LAS __attribute__((address_space(3)))
; __device__ __forceinline__ unsigned pk2(float lo, float hi) { f32x2_t v = {lo, hi}; bf16x2_t b = __builtin_convertvector(v, bf16x2_t); return __builtin_bit_cast(unsigned, b); }
; #define INP(k) karg_in(k)
; #define lane opq(lane_now())
; __device__ __forceinline__ void transpose_item(const float* W, int ldw, int k0, int n0, int nvalid, bf16* WT, int ldt, int drow0, LAS float* scr, int lane, bool late = false) {
;     ...
;     const int c = lane & 7;
; #pragma unroll
;     for (int j = 0; j < 4; ++j) { const int n = (lane >> 3) + 8 * j; const LAS float* s = scr + (8 * c) * 33 + n;
;         u32x4 o; o.x = pk2(s[0 * 33], s[1 * 33]); o.y = pk2(s[2 * 33], s[3 * 33]); o.z = pk2(s[4 * 33], s[5 * 33]); o.w = pk2(s[6 * 33], s[7 * 33]);
;         if (n < nvalid) { if (late) __builtin_nontemporal_store(o, (u32x4*)(WT + (size_t)(drow0 + n) * ldt + k0 + 8 * c)); else *(u32x4*)(WT + (size_t)(drow0 + n) * ldt + k0 + 8 * c) = o; } }
; template <int PART>
; __device__ __forceinline__ void prologue(const Params& P, LAS unsigned char* lds, int gw, int NGW, int wave, int lane) {
;     ...
;           transpose_item(INP(gx ? 19 : 17) + (size_t)n * 128 * 128, 128, kb * 64, nb * 32, 32, (bf16*)(ws + WS_WRG), 128, n * 256 + gx * 128 + nb * 32, scr, lane); }
.LBB0_237:
	ds_read2_b32 v[26:27], v7 offset0:24 offset1:57
	ds_read2_b32 v[28:29], v7 offset0:90 offset1:123
	ds_read2_b32 v[30:31], v7 offset0:156 offset1:189
	ds_read2_b32 v[32:33], v7 offset0:222 offset1:255
	s_waitcnt lgkmcnt(3)
	v_cvt_pk_bf16_f32 v26, v26, v27
	s_waitcnt lgkmcnt(2)
	v_cvt_pk_bf16_f32 v27, v28, v29
	s_waitcnt lgkmcnt(1)
	v_cvt_pk_bf16_f32 v28, v30, v31
	v_add_u32_e32 v30, s20, v42
	v_ashrrev_i32_e32 v31, 31, v30
	v_lshlrev_b64 v[30:31], 8, v[30:31]
	s_waitcnt lgkmcnt(0)
	v_cvt_pk_bf16_f32 v29, v32, v33
	v_lshl_add_u64 v[24:25], v[24:25], 0, v[30:31]
	global_store_dwordx4 v[24:25], v[26:29], off nt

; #define LAS __attribute__((address_space(3)))
; __device__ __forceinline__ unsigned pk2(float lo, float hi) { f32x2_t v = {lo, hi}; bf16x2_t b = __builtin_convertvector(v, bf16x2_t); return __builtin_bit_cast(unsigned, b); }
; #define INP(k) karg_in(k)
; #define lane opq(lane_now())
; __device__ __forceinline__ void transpose_item(const float* W, int ldw, int k0, int n0, int nvalid, bf16* WT, int ldt, int drow0, LAS float* scr, int lane, bool late = false) {
;     ...
;     const int c = lane & 7;
; #pragma unroll
;     for (int j = 0; j < 4; ++j) { const int n = (lane >> 3) + 8 * j; const LAS float* s = scr + (8 * c) * 33 + n;
;         u32x4 o; o.x = pk2(s[0 * 33], s[1 * 33]); o.y = pk2(s[2 * 33], s[3 * 33]); o.z = pk2(s[4 * 33], s[5 * 33]); o.w = pk2(s[6 * 33], s[7 * 33]);
;         if (n < nvalid) { if (late) __builtin_nontemporal_store(o, (u32x4*)(WT + (size_t)(drow0 + n) * ldt + k0 + 8 * c)); else *(u32x4*)(WT + (size_t)(drow0 + n) * ldt + k0 + 8 * c) = o; } }
; template <int PART>
; __device__ __forceinline__ void prologue(const Params& P, LAS unsigned char* lds, int gw, int NGW, int wave, int lane) {
;     ...
;             transpose_item(INP(14), 8208, kb * 64, n0, nv, (bf16*)(ws + WS_WIN), D, dr, scr, lane); continue; }
;         r -= I_IN;
;         if (r < I_BR) { const int which = r / 512; r -= which * 512; const int kb = r / 32, nb = r % 32;
;             transpose_item(INP(26) + (size_t)which * D * D, D, kb * 64, nb * 32, 32, (bf16*)(ws + WS_WBR), D, which * D + nb * 32, scr, lane); continue; }
;         r -= I_BR;
;         if (r < I_OUT) { const int kb = r / 32, nb = r % 32; transpose_item(INP(27), D, kb * 64, nb * 32, 32, (bf16*)(ws + WS_WOUT), D, nb * 32, scr, lane); continue; }
.LBB0_256:
	ds_read2_b32 v[26:27], v7 offset0:24 offset1:57
	ds_read2_b32 v[28:29], v7 offset0:90 offset1:123
	ds_read2_b32 v[30:31], v7 offset0:156 offset1:189
	ds_read2_b32 v[32:33], v7 offset0:222 offset1:255
	s_waitcnt lgkmcnt(3)
	v_cvt_pk_bf16_f32 v26, v26, v27
	s_waitcnt lgkmcnt(2)
	v_cvt_pk_bf16_f32 v27, v28, v29
	s_waitcnt lgkmcnt(1)
	v_cvt_pk_bf16_f32 v28, v30, v31
	v_add_u32_e32 v30, s20, v42
	v_ashrrev_i32_e32 v31, 31, v30
	v_lshlrev_b64 v[30:31], 11, v[30:31]
	s_waitcnt lgkmcnt(0)
	v_cvt_pk_bf16_f32 v29, v32, v33
	v_lshl_add_u64 v[24:25], v[24:25], 0, v[30:31]
	global_store_dwordx4 v[24:25], v[26:29], off nt

; #define LAS __attribute__((address_space(3)))
; __device__ __forceinline__ unsigned pk2(float lo, float hi) { f32x2_t v = {lo, hi}; bf16x2_t b = __builtin_convertvector(v, bf16x2_t); return __builtin_bit_cast(unsigned, b); }
; #define INP(k) karg_in(k)
; #define lane opq(lane_now())
; __device__ __forceinline__ void transpose_item(const float* W, int ldw, int k0, int n0, int nvalid, bf16* WT, int ldt, int drow0, LAS float* scr, int lane, bool late = false) {
;     ...
;     const int c = lane & 7;
; #pragma unroll
;     for (int j = 0; j < 4; ++j) { const int n = (lane >> 3) + 8 * j; const LAS float* s = scr + (8 * c) * 33 + n;
;         u32x4 o; o.x = pk2(s[0 * 33], s[1 * 33]); o.y = pk2(s[2 * 33], s[3 * 33]); o.z = pk2(s[4 * 33], s[5 * 33]); o.w = pk2(s[6 * 33], s[7 * 33]);
;         if (n < nvalid) { if (late) __builtin_nontemporal_store(o, (u32x4*)(WT + (size_t)(drow0 + n) * ldt + k0 + 8 * c)); else *(u32x4*)(WT + (size_t)(drow0 + n) * ldt + k0 + 8 * c) = o; } }
; template <int PART>
; __device__ __forceinline__ void prologue(const Params& P, LAS unsigned char* lds, int gw, int NGW, int wave, int lane) {
;     ...
;             transpose_item(INP(14), 8208, kb * 64, n0, nv, (bf16*)(ws + WS_WIN), D, dr, scr, lane); continue; }
;         r -= I_IN;
;         if (r < I_BR) { const int which = r / 512; r -= which * 512; const int kb = r / 32, nb = r % 32;
;             transpose_item(INP(26) + (size_t)which * D * D, D, kb * 64, nb * 32, 32, (bf16*)(ws + WS_WBR), D, which * D + nb * 32, scr, lane); continue; }
;         r -= I_BR;
;         if (r < I_OUT) { const int kb = r / 32, nb = r % 32; transpose_item(INP(27), D, kb * 64, nb * 32, 32, (bf16*)(ws + WS_WOUT), D, nb * 32, scr, lane); continue; }
.LBB0_297:
	ds_read2_b32 v[26:27], v7 offset0:24 offset1:57
	ds_read2_b32 v[28:29], v7 offset0:90 offset1:123
	ds_read2_b32 v[30:31], v7 offset0:156 offset1:189
	ds_read2_b32 v[32:33], v7 offset0:222 offset1:255
	s_waitcnt lgkmcnt(3)
	v_cvt_pk_bf16_f32 v26, v26, v27
	s_waitcnt lgkmcnt(2)
	v_cvt_pk_bf16_f32 v27, v28, v29
	s_waitcnt lgkmcnt(1)
	v_cvt_pk_bf16_f32 v28, v30, v31
	v_add_u32_e32 v30, s23, v42
	v_ashrrev_i32_e32 v31, 31, v30
	v_lshlrev_b64 v[30:31], 11, v[30:31]
	s_waitcnt lgkmcnt(0)
	v_cvt_pk_bf16_f32 v29, v32, v33
	v_lshl_add_u64 v[24:25], v[24:25], 0, v[30:31]
	global_store_dwordx4 v[24:25], v[26:29], off nt

; #define LAS __attribute__((address_space(3)))
; __device__ __forceinline__ unsigned pk2(float lo, float hi) { f32x2_t v = {lo, hi}; bf16x2_t b = __builtin_convertvector(v, bf16x2_t); return __builtin_bit_cast(unsigned, b); }
; #define INP(k) karg_in(k)
; #define lane opq(lane_now())
; __device__ __forceinline__ void transpose_item(const float* W, int ldw, int k0, int n0, int nvalid, bf16* WT, int ldt, int drow0, LAS float* scr, int lane, bool late = false) {
;     ...
;     const int c = lane & 7;
; #pragma unroll
;     for (int j = 0; j < 4; ++j) { const int n = (lane >> 3) + 8 * j; const LAS float* s = scr + (8 * c) * 33 + n;
;         u32x4 o; o.x = pk2(s[0 * 33], s[1 * 33]); o.y = pk2(s[2 * 33], s[3 * 33]); o.z = pk2(s[4 * 33], s[5 * 33]); o.w = pk2(s[6 * 33], s[7 * 33]);
;         if (n < nvalid) { if (late) __builtin_nontemporal_store(o, (u32x4*)(WT + (size_t)(drow0 + n) * ldt + k0 + 8 * c)); else *(u32x4*)(WT + (size_t)(drow0 + n) * ldt + k0 + 8 * c) = o; } }
; template <int PART>
; __device__ __forceinline__ void prologue(const Params& P, LAS unsigned char* lds, int gw, int NGW, int wave, int lane) {
;     ...
;             transpose_item(INP(14), 8208, kb * 64, n0, nv, (bf16*)(ws + WS_WIN), D, dr, scr, lane); continue; }
;         r -= I_IN;
;         if (r < I_BR) { const int which = r / 512; r -= which * 512; const int kb = r / 32, nb = r % 32;
;             transpose_item(INP(26) + (size_t)which * D * D, D, kb * 64, nb * 32, 32, (bf16*)(ws + WS_WBR), D, which * D + nb * 32, scr, lane); continue; }
;         r -= I_BR;
;         if (r < I_OUT) { const int kb = r / 32, nb = r % 32; transpose_item(INP(27), D, kb * 64, nb * 32, 32, (bf16*)(ws + WS_WOUT), D, nb * 32, scr, lane); continue; }
.LBB0_329:
	ds_read2_b32 v[26:27], v7 offset1:33
	ds_read2_b32 v[28:29], v7 offset0:66 offset1:99
	ds_read2_b32 v[30:31], v7 offset0:132 offset1:165
	ds_read2_b32 v[32:33], v7 offset0:198 offset1:231
	s_waitcnt lgkmcnt(3)
	v_cvt_pk_bf16_f32 v26, v26, v27
	s_waitcnt lgkmcnt(2)
	v_cvt_pk_bf16_f32 v27, v28, v29
	s_waitcnt lgkmcnt(1)
	v_cvt_pk_bf16_f32 v28, v30, v31
	v_add_u32_e32 v30, s23, v1
	v_ashrrev_i32_e32 v31, 31, v30
	v_lshlrev_b64 v[30:31], 11, v[30:31]
	s_waitcnt lgkmcnt(0)
	v_cvt_pk_bf16_f32 v29, v32, v33
	v_lshl_add_u64 v[30:31], v[24:25], 0, v[30:31]
	global_store_dwordx4 v[30:31], v[26:29], off nt
	s_or_b64 exec, exec, s[18:19]
	v_cmp_gt_i32_e32 vcc, s24, v40
	s_and_saveexec_b64 s[18:19], vcc
	s_cbranch_execz .LBB0_295
.LBB0_330:
	ds_read2_b32 v[26:27], v7 offset0:8 offset1:41
	ds_read2_b32 v[28:29], v7 offset0:74 offset1:107
	ds_read2_b32 v[30:31], v7 offset0:140 offset1:173
	ds_read2_b32 v[32:33], v7 offset0:206 offset1:239
	s_waitcnt lgkmcnt(3)
	v_cvt_pk_bf16_f32 v26, v26, v27
	s_waitcnt lgkmcnt(2)
	v_cvt_pk_bf16_f32 v27, v28, v29
	s_waitcnt lgkmcnt(1)
	v_cvt_pk_bf16_f32 v28, v30, v31
	v_add_u32_e32 v30, s23, v40
	v_ashrrev_i32_e32 v31, 31, v30
	v_lshlrev_b64 v[30:31], 11, v[30:31]
	s_waitcnt lgkmcnt(0)
	v_cvt_pk_bf16_f32 v29, v32, v33
	v_lshl_add_u64 v[30:31], v[24:25], 0, v[30:31]
	global_store_dwordx4 v[30:31], v[26:29], off nt
	s_or_b64 exec, exec, s[18:19]
	v_cmp_gt_i32_e32 vcc, s24, v41
	s_and_saveexec_b64 s[18:19], vcc
	s_cbranch_execz .LBB0_296
.LBB0_331:
	ds_read2_b32 v[26:27], v7 offset0:16 offset1:49
	ds_read2_b32 v[28:29], v7 offset0:82 offset1:115
	ds_read2_b32 v[30:31], v7 offset0:148 offset1:181
	ds_read2_b32 v[32:33], v7 offset0:214 offset1:247
	s_waitcnt lgkmcnt(3)
	v_cvt_pk_bf16_f32 v26, v26, v27
	s_waitcnt lgkmcnt(2)
	v_cvt_pk_bf16_f32 v27, v28, v29
	s_waitcnt lgkmcnt(1)
	v_cvt_pk_bf16_f32 v28, v30, v31
	v_add_u32_e32 v30, s23, v41
	v_ashrrev_i32_e32 v31, 31, v30
	v_lshlrev_b64 v[30:31], 11, v[30:31]
	s_waitcnt lgkmcnt(0)
	v_cvt_pk_bf16_f32 v29, v32, v33
	v_lshl_add_u64 v[30:31], v[24:25], 0, v[30:31]
	global_store_dwordx4 v[30:31], v[26:29], off nt
	s_or_b64 exec, exec, s[18:19]
	v_cmp_gt_i32_e32 vcc, s24, v42
	s_and_saveexec_b64 s[18:19], vcc
	s_cbranch_execnz .LBB0_297
	s_branch .LBB0_298
.LBB0_332:
	ds_read2_b32 v[26:27], v7 offset1:33
	ds_read2_b32 v[28:29], v7 offset0:66 offset1:99
	ds_read2_b32 v[30:31], v7 offset0:132 offset1:165
	ds_read2_b32 v[32:33], v7 offset0:198 offset1:231
	s_waitcnt lgkmcnt(3)
	v_cvt_pk_bf16_f32 v26, v26, v27
	s_waitcnt lgkmcnt(2)
	v_cvt_pk_bf16_f32 v27, v28, v29
	s_waitcnt lgkmcnt(1)
	v_cvt_pk_bf16_f32 v28, v30, v31
	v_add_u32_e32 v30, s20, v1
	v_ashrrev_i32_e32 v31, 31, v30
	v_lshlrev_b64 v[30:31], 11, v[30:31]
	s_waitcnt lgkmcnt(0)
	v_cvt_pk_bf16_f32 v29, v32, v33
	v_lshl_add_u64 v[30:31], v[24:25], 0, v[30:31]
	global_store_dwordx4 v[30:31], v[26:29], off nt
	s_or_b64 exec, exec, s[18:19]
	s_and_saveexec_b64 s[18:19], s[6:7]
	s_cbranch_execz .LBB0_264
.LBB0_333:
	ds_read2_b32 v[26:27], v7 offset0:8 offset1:41
	ds_read2_b32 v[28:29], v7 offset0:74 offset1:107
	ds_read2_b32 v[30:31], v7 offset0:140 offset1:173
	ds_read2_b32 v[32:33], v7 offset0:206 offset1:239
	s_waitcnt lgkmcnt(3)
	v_cvt_pk_bf16_f32 v26, v26, v27
	s_waitcnt lgkmcnt(2)
	v_cvt_pk_bf16_f32 v27, v28, v29
	s_waitcnt lgkmcnt(1)
	v_cvt_pk_bf16_f32 v28, v30, v31
	v_add_u32_e32 v30, s20, v40
	v_ashrrev_i32_e32 v31, 31, v30
	v_lshlrev_b64 v[30:31], 11, v[30:31]
	s_waitcnt lgkmcnt(0)
	v_cvt_pk_bf16_f32 v29, v32, v33
	v_lshl_add_u64 v[30:31], v[24:25], 0, v[30:31]
	global_store_dwordx4 v[30:31], v[26:29], off nt
	s_or_b64 exec, exec, s[18:19]
	s_and_saveexec_b64 s[18:19], s[8:9]
	s_cbranch_execz .LBB0_265
.LBB0_334:
	ds_read2_b32 v[26:27], v7 offset0:16 offset1:49
	ds_read2_b32 v[28:29], v7 offset0:82 offset1:115
	ds_read2_b32 v[30:31], v7 offset0:148 offset1:181
	ds_read2_b32 v[32:33], v7 offset0:214 offset1:247
	s_waitcnt lgkmcnt(3)
	v_cvt_pk_bf16_f32 v26, v26, v27
	s_waitcnt lgkmcnt(2)
	v_cvt_pk_bf16_f32 v27, v28, v29
	s_waitcnt lgkmcnt(1)
	v_cvt_pk_bf16_f32 v28, v30, v31
	v_add_u32_e32 v30, s20, v41
	v_ashrrev_i32_e32 v31, 31, v30
	v_lshlrev_b64 v[30:31], 11, v[30:31]
	s_waitcnt lgkmcnt(0)
	v_cvt_pk_bf16_f32 v29, v32, v33
	v_lshl_add_u64 v[30:31], v[24:25], 0, v[30:31]
	global_store_dwordx4 v[30:31], v[26:29], off nt
	s_or_b64 exec, exec, s[18:19]
	s_and_saveexec_b64 s[18:19], s[10:11]
	s_cbranch_execnz .LBB0_266
	s_branch .LBB0_267

; #define LAS __attribute__((address_space(3)))
; __device__ __forceinline__ unsigned pk2(float lo, float hi) { f32x2_t v = {lo, hi}; bf16x2_t b = __builtin_convertvector(v, bf16x2_t); return __builtin_bit_cast(unsigned, b); }
; #define INP(k) karg_in(k)
; #define lane opq(lane_now())
; __device__ __forceinline__ void transpose_item(const float* W, int ldw, int k0, int n0, int nvalid, bf16* WT, int ldt, int drow0, LAS float* scr, int lane, bool late = false) {
;     ...
;     const int c = lane & 7;
; #pragma unroll
;     for (int j = 0; j < 4; ++j) { const int n = (lane >> 3) + 8 * j; const LAS float* s = scr + (8 * c) * 33 + n;
;         u32x4 o; o.x = pk2(s[0 * 33], s[1 * 33]); o.y = pk2(s[2 * 33], s[3 * 33]); o.z = pk2(s[4 * 33], s[5 * 33]); o.w = pk2(s[6 * 33], s[7 * 33]);
;         if (n < nvalid) { if (late) __builtin_nontemporal_store(o, (u32x4*)(WT + (size_t)(drow0 + n) * ldt + k0 + 8 * c)); else *(u32x4*)(WT + (size_t)(drow0 + n) * ldt + k0 + 8 * c) = o; } }
; template <int PART>
; __device__ __forceinline__ void prologue(const Params& P, LAS unsigned char* lds, int gw, int NGW, int wave, int lane) {
;     ...
;           transpose_item(INP(gx ? 19 : 17) + (size_t)n * 128 * 128, 128, kb * 64, nb * 32, 32, (bf16*)(ws + WS_WRG), 128, n * 256 + gx * 128 + nb * 32, scr, lane); }
.LBB0_339:
	ds_read2_b32 v[26:27], v7 offset1:33
	ds_read2_b32 v[28:29], v7 offset0:66 offset1:99
	ds_read2_b32 v[30:31], v7 offset0:132 offset1:165
	ds_read2_b32 v[32:33], v7 offset0:198 offset1:231
	s_waitcnt lgkmcnt(3)
	v_cvt_pk_bf16_f32 v26, v26, v27
	s_waitcnt lgkmcnt(2)
	v_cvt_pk_bf16_f32 v27, v28, v29
	s_waitcnt lgkmcnt(1)
	v_cvt_pk_bf16_f32 v28, v30, v31
	v_add_u32_e32 v30, s20, v1
	v_ashrrev_i32_e32 v31, 31, v30
	v_lshlrev_b64 v[30:31], 8, v[30:31]
	s_waitcnt lgkmcnt(0)
	v_cvt_pk_bf16_f32 v29, v32, v33
	v_lshl_add_u64 v[30:31], v[24:25], 0, v[30:31]
	global_store_dwordx4 v[30:31], v[26:29], off nt
	s_or_b64 exec, exec, s[18:19]
	s_and_saveexec_b64 s[18:19], s[6:7]
	s_cbranch_execz .LBB0_235
.LBB0_340:
	ds_read2_b32 v[26:27], v7 offset0:8 offset1:41
	ds_read2_b32 v[28:29], v7 offset0:74 offset1:107
	ds_read2_b32 v[30:31], v7 offset0:140 offset1:173
	ds_read2_b32 v[32:33], v7 offset0:206 offset1:239
	s_waitcnt lgkmcnt(3)
	v_cvt_pk_bf16_f32 v26, v26, v27
	s_waitcnt lgkmcnt(2)
	v_cvt_pk_bf16_f32 v27, v28, v29
	s_waitcnt lgkmcnt(1)
	v_cvt_pk_bf16_f32 v28, v30, v31
	v_add_u32_e32 v30, s20, v40
	v_ashrrev_i32_e32 v31, 31, v30
	v_lshlrev_b64 v[30:31], 8, v[30:31]
	s_waitcnt lgkmcnt(0)
	v_cvt_pk_bf16_f32 v29, v32, v33
	v_lshl_add_u64 v[30:31], v[24:25], 0, v[30:31]
	global_store_dwordx4 v[30:31], v[26:29], off nt
	s_or_b64 exec, exec, s[18:19]
	s_and_saveexec_b64 s[18:19], s[8:9]
	s_cbranch_execz .LBB0_236
.LBB0_341:
	ds_read2_b32 v[26:27], v7 offset0:16 offset1:49
	ds_read2_b32 v[28:29], v7 offset0:82 offset1:115
	ds_read2_b32 v[30:31], v7 offset0:148 offset1:181
	ds_read2_b32 v[32:33], v7 offset0:214 offset1:247
	s_waitcnt lgkmcnt(3)
	v_cvt_pk_bf16_f32 v26, v26, v27
	s_waitcnt lgkmcnt(2)
	v_cvt_pk_bf16_f32 v27, v28, v29
	s_waitcnt lgkmcnt(1)
	v_cvt_pk_bf16_f32 v28, v30, v31
	v_add_u32_e32 v30, s20, v41
	v_ashrrev_i32_e32 v31, 31, v30
	v_lshlrev_b64 v[30:31], 8, v[30:31]
	s_waitcnt lgkmcnt(0)
	v_cvt_pk_bf16_f32 v29, v32, v33
	v_lshl_add_u64 v[30:31], v[24:25], 0, v[30:31]
	global_store_dwordx4 v[30:31], v[26:29], off nt
	s_or_b64 exec, exec, s[18:19]
	s_and_saveexec_b64 s[18:19], s[10:11]
	s_cbranch_execnz .LBB0_237
	s_branch .LBB0_238
